# v37 + scan A1: scalar f16 token-shift/tanh-input sequences packed (v_pk_add/fma_f16 + fma_mix op_sel), -19 instr/iter
# speedup vs baseline: 1.0138x; 1.0014x over previous
.LBB0_538:
	s_sub_i32 s22, s28, s29
	s_min_u32 s24, s22, 64
	s_lshr_b32 s22, s24, 4
	s_cmp_lt_u32 s68, s22
	s_cselect_b64 s[34:35], -1, 0
	s_cmp_ge_u32 s68, s22
	s_cbranch_scc1 .LBB0_542
	ds_read_b64 v[24:25], v207
	ds_read_b64 v[34:35], v132
	ds_read_b64 v[8:9], v208
	ds_read_b64 v[26:27], v209
	ds_read_b64 v[36:37], v210
	ds_read2_b64 v[20:23], v135 offset1:32
	ds_read_b64 v[38:39], v134
	ds_read_b64 v[28:29], v136
	ds_read_b64 v[40:41], v211
	ds_read_b64 v[42:43], v131
	ds_read_b64 v[32:33], v212
	s_waitcnt lgkmcnt(7)
	v_pk_add_f16 v11, v26, v24 neg_lo:[0,1] neg_hi:[0,1]
	v_pk_add_f16 v26, v27, v25 neg_lo:[0,1] neg_hi:[0,1]
	s_waitcnt lgkmcnt(3)
	v_pk_fma_f16 v66, v11, v28, v24
	v_pk_fma_f16 v67, v26, v29, v25
	ds_read_b64 v[68:69], v133
	ds_read2_b64 v[28:31], v135 offset0:96 offset1:112
	s_waitcnt lgkmcnt(4)
	v_pk_add_f16 v11, v36, v40 neg_lo:[0,1] neg_hi:[0,1]
	v_pk_add_f16 v70, v37, v41 neg_lo:[0,1] neg_hi:[0,1]
	v_pk_add_f16 v38, v38, v34 neg_lo:[0,1] neg_hi:[0,1]
	s_waitcnt lgkmcnt(1)
	v_pk_add_f16 v24, v68, v42 neg_lo:[0,1] neg_hi:[0,1]
	v_pk_add_f16 v25, v69, v43 neg_lo:[0,1] neg_hi:[0,1]
	s_waitcnt lgkmcnt(0)
	v_pk_fma_f16 v24, v24, v28, v42
	v_pk_fma_f16 v25, v25, v29, v43
	v_fma_mix_f32 v36, v24, s86, 0 op_sel_hi:[1,0,0]
	v_fma_mix_f32 v43, v24, s86, 0 op_sel:[1,0,0] op_sel_hi:[1,0,0]
	v_fma_mix_f32 v37, v25, s86, 0 op_sel_hi:[1,0,0]
	v_fma_mix_f32 v42, v25, s86, 0 op_sel:[1,0,0] op_sel_hi:[1,0,0]
	ds_read2_b64 v[24:27], v135 offset0:64 offset1:80
	v_exp_f32_e32 v36, v36
	v_exp_f32_e32 v43, v43
	v_exp_f32_e32 v37, v37
	v_exp_f32_e32 v42, v42
	v_add_f32_e32 v28, 1.0, v36
	v_add_f32_e32 v36, 1.0, v43
	v_rcp_f32_e32 v28, v28
	v_rcp_f32_e32 v29, v36
	s_waitcnt lgkmcnt(0)
	v_pk_mul_f16 v69, v67, v25
	v_add_f32_e32 v36, 1.0, v37
	v_add_f32_e32 v37, 1.0, v42
	v_rcp_f32_e32 v36, v36
	v_rcp_f32_e32 v37, v37
	v_pk_mul_f16 v68, v66, v24
	v_pk_fma_f32 v[24:25], v[28:29], -2.0, 1.0 op_sel_hi:[1,0,0]
	v_pk_add_f16 v39, v39, v35 neg_lo:[0,1] neg_hi:[0,1]
	v_pk_fma_f32 v[28:29], v[36:37], -2.0, 1.0 op_sel_hi:[1,0,0]
	v_pk_fma_f16 v31, v39, v31, v35
	v_cvt_pk_f16_f32 v29, v28, v29
	v_cvt_pk_f16_f32 v28, v24, v25
	v_pk_fma_f16 v30, v38, v30, v34
	ds_write_b64 v109, v[28:29] offset:56320
	v_pk_fma_f16 v23, v70, v23, v41
	v_pk_fma_f16 v22, v11, v22, v40
	ds_write_b64 v213, v[30:31]
	ds_write_b64 v214, v[22:23] offset:9216
	ds_read_b64 v[28:29], v215
	ds_read_b64 v[42:43], v138
	ds_read_b64 v[34:35], v216
	ds_read_b64 v[30:31], v217
	ds_read_b64 v[72:73], v218
	ds_read2_b64 v[22:25], v141 offset1:32
	ds_read_b64 v[74:75], v140
	ds_read_b64 v[38:39], v142
	ds_read_b64 v[76:77], v219
	ds_read_b64 v[78:79], v137
	s_waitcnt lgkmcnt(12)
	ds_read_b64 v[36:37], v220
	s_waitcnt lgkmcnt(7)
	v_pk_add_f16 v30, v30, v28 neg_lo:[0,1] neg_hi:[0,1]
	v_pk_add_f16 v31, v31, v29 neg_lo:[0,1] neg_hi:[0,1]
	s_waitcnt lgkmcnt(3)
	v_pk_fma_f16 v70, v30, v38, v28
	v_pk_fma_f16 v71, v31, v39, v29
	ds_read_b64 v[80:81], v139
	ds_read2_b64 v[38:41], v141 offset0:96 offset1:112
	s_waitcnt lgkmcnt(4)
	v_pk_add_f16 v82, v72, v76 neg_lo:[0,1] neg_hi:[0,1]
	v_pk_add_f16 v83, v73, v77 neg_lo:[0,1] neg_hi:[0,1]
	v_pk_add_f16 v84, v74, v42 neg_lo:[0,1] neg_hi:[0,1]
	s_waitcnt lgkmcnt(1)
	v_pk_add_f16 v85, v75, v43 neg_lo:[0,1] neg_hi:[0,1]
	v_pk_add_f16 v28, v80, v78 neg_lo:[0,1] neg_hi:[0,1]
	v_pk_add_f16 v29, v81, v79 neg_lo:[0,1] neg_hi:[0,1]
	s_waitcnt lgkmcnt(0)
	v_pk_fma_f16 v28, v28, v38, v78
	v_pk_fma_f16 v29, v29, v39, v79
	v_fma_mix_f32 v72, v28, s86, 0 op_sel_hi:[1,0,0]
	v_fma_mix_f32 v73, v28, s86, 0 op_sel:[1,0,0] op_sel_hi:[1,0,0]
	v_fma_mix_f32 v74, v29, s86, 0 op_sel_hi:[1,0,0]
	v_fma_mix_f32 v75, v29, s86, 0 op_sel:[1,0,0] op_sel_hi:[1,0,0]
	ds_read2_b64 v[28:31], v141 offset0:64 offset1:80
	v_exp_f32_e32 v72, v72
	v_exp_f32_e32 v73, v73
	v_exp_f32_e32 v74, v74
	v_exp_f32_e32 v75, v75
	v_add_f32_e32 v38, 1.0, v72
	v_add_f32_e32 v39, 1.0, v73
	v_add_f32_e32 v74, 1.0, v74
	v_add_f32_e32 v75, 1.0, v75
	v_rcp_f32_e32 v38, v38
	v_rcp_f32_e32 v39, v39
	v_rcp_f32_e32 v74, v74
	v_rcp_f32_e32 v75, v75
	v_mov_b32_e32 v11, v10
	s_waitcnt lgkmcnt(0)
	v_pk_mul_f16 v73, v71, v29
	v_pk_mul_f16 v72, v70, v28
	v_pk_fma_f32 v[28:29], v[38:39], -2.0, 1.0 op_sel_hi:[1,0,0]
	v_pk_fma_f32 v[38:39], v[74:75], -2.0, 1.0 op_sel_hi:[1,0,0]
	v_pk_fma_f16 v75, v83, v25, v77
	v_dot2c_f32_f16_e32 v11, v68, v68
	v_pk_fma_f16 v74, v82, v24, v76
	v_pk_fma_f16 v40, v84, v40, v42
	v_dot2c_f32_f16_e32 v11, v69, v69
	v_dot2c_f32_f16_e32 v11, v72, v72
	v_dot2c_f32_f16_e32 v11, v73, v73
	v_pk_fma_f16 v41, v85, v41, v43
	s_nop 1
	ds_bpermute_b32 v43, v221, v11
	v_cvt_pk_f16_f32 v25, v38, v39
	v_cvt_pk_f16_f32 v24, v28, v29
	ds_write_b64 v113, v[24:25] offset:56320
	s_waitcnt lgkmcnt(1)
	v_add_f32_e32 v11, v11, v43
	ds_bpermute_b32 v24, v222, v11
	ds_write_b64 v223, v[40:41]
	ds_write_b64 v224, v[74:75] offset:9216
	s_waitcnt lgkmcnt(2)
	s_and_saveexec_b64 s[22:23], s[0:1]
	s_cbranch_execz .LBB0_541
	s_waitcnt lgkmcnt(0)
	v_add_f32_e32 v11, v11, v24
	v_add_u32_e32 v24, s80, v97
	ds_write_b32 v24, v11
